# mixer-A unit prologue: redundant vmcnt(0) drain before the q loads removed (later counted wait covers it)
# baseline (speedup 1.0000x reference)
; __device__ __forceinline__ void unitA(LAS char* lds, const gbf* PROJ, const gbf* VT, gbf* Y, const int S, const int tok0, const int h, const int qblk,
;                                       const float lam, const float oml, const gfl* subln, const float kn2a, const float kn2b, const int tid_) {
;     const int tid = opaque_v(tid_);
;     const int lane = tid & 63, r32 = lane & 31, hi = lane >> 5, wid = __builtin_amdgcn_readfirstlane(tid >> 6), rg = wid >> 1, map = wid & 1;
;     const int NT = S >> 6, tstart = qblk * 2;
;     const int q0 = qblk * 128 + rg * 32;
;     const float slope2 = LOG2E * __builtin_amdgcn_exp2f(-2.f * (float)(h + 1)), nslope = -slope2, inv_slope2 = 1.f / slope2;
;     const bool skip_en = slope2 * (float)S > SKIP_MARGIN + 8.f;
;     LAS float* wsf = (LAS float*)(lds + WSFA_OFF) + wid * 64;
;     LAS float* lim = (LAS float*)(lds + LIM_OFF);
;     asm volatile("s_waitcnt vmcnt(0)" ::: "memory");
;     const gbf* ksrc[2]; const gbf* vsrc[2];
; #pragma unroll
;     for (int i = 0; i < 2; ++i) { const int j = 2 * wid + i;
; __global__ void __launch_bounds__(512, 2) mega_fwd(Params p) {
;     ...
;                       const unsigned x = (xme + sx) & 7u;
;                       GAS unsigned* qh = (GAS unsigned*)(ws + WS_Q) + ((g * 2 + l) * 16 + (int)x) * 16;
;                       for (;;) {
;                           if (tid == 0) *qs = __hip_atomic_fetch_add(qh, 1u, __ATOMIC_RELAXED, __HIP_MEMORY_SCOPE_AGENT);
;                           __syncthreads();
;                           const unsigned j = (unsigned)__builtin_amdgcn_readfirstlane((int)*qs);
;                           __syncthreads();
;                           if (j >= 256u) break;
;                           const int r = (int)(j >> 5), i = ((3 - (r >> 1)) & 3) + 4 * (r & 1), c = ((int)(j & 31u) + 4 * i) & 31, top = i >> 2, h = i & 3;
;                           int b, qblk;
;                           if (NQA == 32) { b = 2 * (int)x + top; qblk = c; } else { b = (int)x; qblk = c + 32 * top; }
;                           const u32x4 kq = *(const GAS u32x4*)(kn2 + b * 16 + h * 4);
;                           const float kn2a = __uint_as_float(kq.x) + __uint_as_float(kq.y), kn2b = __uint_as_float(kq.z) + __uint_as_float(kq.w);
;                           att::unitA((LAS char*)lds, uni(PROJ), uni(VT), uni(Y), S, b * S, h, qblk, lam, oml, subln, unif(kn2a), unif(kn2b), tid);
.LBB0_364:
	s_or_b64 exec, exec, s[4:5]
	v_mov_b32_e32 v0, s15
	s_waitcnt lgkmcnt(0)
	s_barrier
	ds_read_b32 v0, v0
	s_mov_b64 s[4:5], -1
	s_waitcnt lgkmcnt(0)
	s_barrier
	v_readfirstlane_b32 s0, v0
	s_cmpk_gt_u32 s0, 0xff
	s_cbranch_scc1 .LBB0_359
	s_lshr_b32 s4, s0, 3
	s_lshr_b32 s2, s0, 6
	s_and_b32 s4, s4, 4
	s_sub_i32 s2, s4, s2
	s_add_i32 s2, s2, 3
	s_lshl_b32 s4, s2, 2
	s_add_i32 s4, s4, s0
	s_and_b32 s0, s4, 31
	s_lshr_b32 s4, s2, 2
	s_and_b32 s10, s2, 3
	s_add_i32 s2, s4, s1
	s_lshl_b32 s8, s4, 5
	s_and_b64 s[4:5], s[94:95], exec
	s_cselect_b32 s4, 0, s8
	s_or_b32 s24, s0, s4
	s_and_b64 s[4:5], s[94:95], exec
	s_cselect_b32 s0, s2, s90
	s_lshl_b32 s76, s0, 4
	s_lshl_b64 s[4:5], s[76:77], 2
	s_add_u32 s4, s40, s4
	s_addc_u32 s5, s41, s5
	s_lshl_b32 s2, s10, 4
	v_mov_b32_e32 v0, s2
	global_load_dwordx4 v[2:5], v0, s[4:5]
	v_mov_b32_e32 v10, v205
	s_lshl_b32 s11, s0, s87
	s_not_b32 s2, s10
	v_readfirstlane_b32 s0, v10
	s_ashr_i32 s12, s0, 6
	s_ashr_i32 s33, s0, 7
	s_lshl_b32 s88, s33, 5
	s_lshl_b32 s13, s2, 1
	s_and_b32 s2, s0, 0x3fffffc0
	s_lshl_b32 s16, s12, 1
	s_lshl_b32 s0, s10, 7
	s_lshl_b32 s4, s11, 1
	s_add_u32 s4, s34, s4
	v_bfe_u32 v11, v10, 4, 2
	s_addc_u32 s5, s35, 0
	s_lshl_b32 s20, s12, 3
	v_or_b32_e32 v0, s20, v11
	v_bitop3_b32 v13, s20, v10, v11 bitop3:0x36
	v_add_u32_e32 v0, s11, v0
	v_mov_b64_e32 v[6:7], s[92:93]
	s_movk_i32 s17, 0x1e00
	v_mad_i64_i32 v[8:9], s[8:9], v0, s17, v[6:7]
	s_lshl_b32 s76, s10, 8
	v_lshlrev_b32_e32 v0, 4, v13
	v_bfe_u32 v12, v10, 3, 3
	v_lshl_add_u64 v[8:9], v[8:9], 0, s[76:77]
	v_and_b32_e32 v0, 0xf0, v0
	v_lshl_add_u64 v[180:181], v[8:9], 0, v[0:1]
	v_or_b32_e32 v8, s0, v12
	v_lshl_add_u32 v8, s12, 4, v8
	v_xor_b32_e32 v0, v11, v10
	v_ashrrev_i32_e32 v9, 31, v8
	v_lshlrev_b64 v[8:9], 17, v[8:9]
	v_lshlrev_b32_e32 v0, 4, v0
	s_or_b32 s10, s16, 1
	v_lshl_add_u64 v[8:9], s[4:5], 0, v[8:9]
	v_and_b32_e32 v0, 0x70, v0
	s_lshl_b32 s8, s10, 2
	v_lshl_add_u64 v[182:183], v[8:9], 0, v[0:1]
	v_or_b32_e32 v0, s8, v11
	v_bitop3_b32 v11, s8, v10, v11 bitop3:0x36
	v_add_u32_e32 v0, s11, v0
	v_mad_i64_i32 v[8:9], s[8:9], v0, s17, v[6:7]
	v_lshlrev_b32_e32 v0, 4, v11
	v_lshl_add_u64 v[8:9], v[8:9], 0, s[76:77]
	v_and_b32_e32 v0, 0xf0, v0
	v_lshl_add_u64 v[196:197], v[8:9], 0, v[0:1]
	v_lshl_or_b32 v0, s10, 3, v12
	v_lshrrev_b32_e32 v8, 1, v0
	v_xor_b32_e32 v11, v8, v10
	v_add_u32_e32 v8, s0, v0
	v_ashrrev_i32_e32 v9, 31, v8
	v_lshlrev_b64 v[8:9], 17, v[8:9]
	v_lshl_add_u64 v[8:9], s[4:5], 0, v[8:9]
	s_lshl_b32 s5, s24, 7
	v_lshlrev_b32_e32 v0, 4, v11
	s_add_i32 s88, s88, s5
	v_and_b32_e32 v178, 31, v10
	v_and_b32_e32 v0, 0x70, v0
	s_add_i32 s86, s88, s11
	v_lshl_add_u64 v[198:199], v[8:9], 0, v[0:1]
	v_or_b32_e32 v0, s86, v178
	s_and_b32 s4, s12, 1
	v_mad_i64_i32 v[6:7], s[8:9], v0, s17, v[6:7]
	v_bfe_u32 v210, v10, 5, 1
	v_lshl_add_u64 v[6:7], v[6:7], 0, s[76:77]
	s_lshl_b32 s76, s4, 7
	v_lshl_add_u64 v[6:7], v[6:7], 0, s[76:77]
	v_lshlrev_b32_e32 v0, 4, v210
	v_lshl_add_u64 v[6:7], v[6:7], 0, v[0:1]
	global_load_dwordx4 v[162:165], v[6:7], off
	global_load_dwordx4 v[166:169], v[6:7], off offset:32
	global_load_dwordx4 v[170:173], v[6:7], off offset:64
	global_load_dwordx4 v[174:177], v[6:7], off offset:96
	s_mov_b32 s8, 0x43100000
	s_waitcnt vmcnt(4)
	v_add_f32_e32 v2, v2, v3
	v_cvt_f32_i32_e32 v3, s13
	v_readfirstlane_b32 s13, v2
	v_add_f32_e32 v4, v4, v5
	s_lshl_b32 s76, s24, 8
	v_exp_f32_e32 v2, v3
	v_readfirstlane_b32 s16, v4
	v_lshlrev_b32_e32 v8, 3, v210
	v_cvt_f32_i32_e32 v239, s88
	v_mul_f32_e32 v211, 0x3fb8aa3b, v2
	v_mul_f32_e32 v2, v211, v209
	v_cmp_lt_f32_e64 s[8:9], s8, v2
	v_div_scale_f32 v2, s[10:11], v211, v211, 1.0
	v_rcp_f32_e32 v3, v2
	s_lshl_b32 s10, s12, 11
	s_add_i32 s91, s10, 0
	s_mov_b32 m0, s91
	v_fma_f32 v4, -v2, v3, 1.0
	v_fmac_f32_e32 v3, v4, v3
	v_div_scale_f32 v4, vcc, 1.0, v211, 1.0
	v_mul_f32_e32 v5, v4, v3
	v_fma_f32 v6, -v2, v5, v4
	v_fmac_f32_e32 v5, v6, v3
	v_fma_f32 v2, -v2, v5, v4
	v_div_fmas_f32 v2, v2, v3, v5
	v_div_fixup_f32 v212, v2, v211, 1.0
	v_mad_u64_u32 v[2:3], s[10:11], s5, v228, v[180:181]
	v_lshl_add_u64 v[2:3], v[2:3], 0, s[80:81]
	global_load_lds_dwordx4 v[2:3], off
	v_mad_u64_u32 v[2:3], s[10:11], s5, v228, v[196:197]
	v_lshl_add_u64 v[2:3], v[2:3], 0, s[80:81]
	s_add_i32 m0, s91, 0x400
	s_or_b32 s5, s5, 64
	global_load_lds_dwordx4 v[2:3], off
	v_lshl_add_u64 v[2:3], v[182:183], 0, s[76:77]
	s_add_i32 m0, s91, 0x4000
	v_lshl_add_u64 v[4:5], v[198:199], 0, s[76:77]
	global_load_lds_dwordx4 v[2:3], off
	s_add_i32 m0, s91, 0x4400
	v_mad_u64_u32 v[6:7], s[10:11], s5, v228, v[180:181]
	global_load_lds_dwordx4 v[4:5], off
	s_add_i32 m0, s91, 0x8000
	v_lshl_add_u64 v[6:7], v[6:7], 0, s[80:81]
	global_load_lds_dwordx4 v[6:7], off
	v_mad_u64_u32 v[6:7], s[10:11], s5, v228, v[196:197]
	v_lshl_add_u64 v[6:7], v[6:7], 0, s[80:81]
	s_add_i32 m0, s91, 0x8400
	v_lshl_add_u64 v[2:3], v[2:3], 0, s[78:79]
	global_load_lds_dwordx4 v[6:7], off
	s_add_i32 m0, s91, 0xc000
	s_mov_b32 s5, 0xf800000
	global_load_lds_dwordx4 v[2:3], off
	v_lshl_add_u64 v[2:3], v[4:5], 0, s[78:79]
	s_add_i32 m0, s91, 0xc400
	s_cmp_eq_u32 s4, 0
	global_load_lds_dwordx4 v[2:3], off
	s_cselect_b64 s[10:11], -1, 0
	s_cmp_eq_u32 s4, 1
	v_and_b32_e32 v179, 63, v10
	v_mov_b32_e32 v16, v1
	v_mov_b32_e32 v17, v1
	v_xor_b32_e32 v200, 0x80000000, v211
	s_waitcnt vmcnt(0)
; __device__ __forceinline__ float bf_lo(unsigned w) { return __uint_as_float(w << 16); }
; __device__ __forceinline__ float bf_hi(unsigned w) { return __uint_as_float(w & 0xffff0000u); }
; __device__ __forceinline__ float sum_x32(float v) { auto rr = __builtin_amdgcn_permlane32_swap(__float_as_uint(v), __float_as_uint(v), false, false); return __uint_as_float(rr[0]) + __uint_as_float(rr[1]); }
; __device__ __forceinline__ int swap23(int r) { return (r & ~12) | ((r & 4) << 1) | ((r & 8) >> 1); }
; __device__ __forceinline__ void unitA(LAS char* lds, const gbf* PROJ, const gbf* VT, gbf* Y, const int S, const int tok0, const int h, const int qblk,
;                                       const float lam, const float oml, const gfl* subln, const float kn2a, const float kn2b, const int tid_) {
;     ...
;     { float qn = 0.f;
; #pragma unroll
;       for (int dc = 0; dc < 4; ++dc) { const u32x4 w = __builtin_bit_cast(u32x4, qf[dc]);
;           qn += bf_lo(w.x) * bf_lo(w.x) + bf_hi(w.x) * bf_hi(w.x) + bf_lo(w.y) * bf_lo(w.y) + bf_hi(w.y) * bf_hi(w.y) + bf_lo(w.z) * bf_lo(w.z) + bf_hi(w.z) * bf_hi(w.z) + bf_lo(w.w) * bf_lo(w.w) + bf_hi(w.w) * bf_hi(w.w); }
;       qn = sum_x32(qn);
;       ub = __builtin_sqrtf(qn * ((map ? kn2b : kn2a) * 1.03f)) * 1.002f + 0.05f; }
;     f32x16 o[4];
; #pragma unroll
;     for (int d = 0; d < 4; ++d)
; #pragma unroll
;         for (int r = 0; r < 16; ++r) o[d][r] = 0.f;
;     float mref = 0.f, lsum = 0.f;
;     int kbase[4], vbase[4];
;     { const int krow = swap23(r32), km = krow & 15, vm = (r32 >> 1) & 7;
; #pragma unroll
;       for (int dc = 0; dc < 4; ++dc) kbase[dc] = krow * 256 + (((map * 8 + dc * 2 + hi) ^ km) << 4);
; #pragma unroll
;       for (int c = 0; c < 4; ++c) vbase[c] = A_VOFF + r32 * 128 + (((2 * c + hi) ^ vm) << 4); }
;     const float qposf = (float)(q0 + r32 - 8 * hi);
	v_and_b32_e32 v5, 0xffff0000, v162
	v_lshlrev_b32_e32 v4, 16, v162
	v_mul_f32_e32 v5, v5, v5
	v_fmac_f32_e32 v5, v4, v4
	v_lshlrev_b32_e32 v4, 16, v163
	v_fmac_f32_e32 v5, v4, v4
	v_and_b32_e32 v4, 0xffff0000, v163
	v_fmac_f32_e32 v5, v4, v4
	v_lshlrev_b32_e32 v4, 16, v164
	v_fmac_f32_e32 v5, v4, v4
	v_and_b32_e32 v4, 0xffff0000, v164
	v_fmac_f32_e32 v5, v4, v4
	v_lshlrev_b32_e32 v4, 16, v165
	v_fmac_f32_e32 v5, v4, v4
	v_and_b32_e32 v4, 0xffff0000, v165
	v_and_b32_e32 v6, 0xffff0000, v166
	v_fmac_f32_e32 v5, v4, v4
	v_lshlrev_b32_e32 v4, 16, v166
	v_mul_f32_e32 v6, v6, v6
	v_fmac_f32_e32 v6, v4, v4
	v_lshlrev_b32_e32 v4, 16, v167
	v_fmac_f32_e32 v6, v4, v4
	v_and_b32_e32 v4, 0xffff0000, v167
	v_fmac_f32_e32 v6, v4, v4
	v_lshlrev_b32_e32 v4, 16, v168
	v_fmac_f32_e32 v6, v4, v4
	v_and_b32_e32 v4, 0xffff0000, v168
	v_fmac_f32_e32 v6, v4, v4
	v_lshlrev_b32_e32 v4, 16, v169
	v_fmac_f32_e32 v6, v4, v4
	v_and_b32_e32 v4, 0xffff0000, v169
	v_fmac_f32_e32 v6, v4, v4
	v_add_f32_e32 v4, v5, v6
	v_and_b32_e32 v6, 0xffff0000, v170
	v_lshlrev_b32_e32 v5, 16, v170
	v_mul_f32_e32 v6, v6, v6
	v_fmac_f32_e32 v6, v5, v5
	v_lshlrev_b32_e32 v5, 16, v171
	v_fmac_f32_e32 v6, v5, v5
	v_and_b32_e32 v5, 0xffff0000, v171
	v_fmac_f32_e32 v6, v5, v5
	v_lshlrev_b32_e32 v5, 16, v172
	v_fmac_f32_e32 v6, v5, v5
	v_and_b32_e32 v5, 0xffff0000, v172
	v_fmac_f32_e32 v6, v5, v5
	v_lshlrev_b32_e32 v5, 16, v173
	v_fmac_f32_e32 v6, v5, v5
	v_and_b32_e32 v5, 0xffff0000, v173
	v_fmac_f32_e32 v6, v5, v5
	v_add_f32_e32 v4, v4, v6
	v_and_b32_e32 v6, 0xffff0000, v174
	v_lshlrev_b32_e32 v5, 16, v174
	v_mul_f32_e32 v6, v6, v6
	v_fmac_f32_e32 v6, v5, v5
	v_lshlrev_b32_e32 v5, 16, v175
	v_fmac_f32_e32 v6, v5, v5
	v_and_b32_e32 v5, 0xffff0000, v175
	v_fmac_f32_e32 v6, v5, v5
	v_lshlrev_b32_e32 v5, 16, v176
	v_fmac_f32_e32 v6, v5, v5
	v_and_b32_e32 v5, 0xffff0000, v176
	v_fmac_f32_e32 v6, v5, v5
	v_lshlrev_b32_e32 v5, 16, v177
	v_fmac_f32_e32 v6, v5, v5
	v_and_b32_e32 v5, 0xffff0000, v177
	v_fmac_f32_e32 v6, v5, v5
	v_add_f32_e32 v4, v4, v6
	v_mov_b32_e32 v5, v4
	s_nop 1
	v_permlane32_swap_b32_e32 v4, v5
	v_add_f32_e32 v4, v4, v5
	v_mov_b32_e32 v5, s16
	v_mov_b32_e32 v6, s13
	v_cndmask_b32_e64 v5, v5, v6, s[10:11]
	v_mul_f32_e32 v5, 0x3f83d70a, v5
	v_mul_f32_e32 v4, v5, v4
	v_mul_f32_e32 v5, 0x4f800000, v4
	v_cmp_gt_f32_e32 vcc, s5, v4
	s_cselect_b64 s[16:17], -1, 0
	s_lshl_b32 s2, s2, 2
	v_cndmask_b32_e32 v4, v4, v5, vcc
	v_sqrt_f32_e32 v5, v4
	s_add_i32 s42, s2, 0
	s_lshl_b32 s2, s4, 3
	s_add_i32 s42, s42, 0x20000
	v_add_u32_e32 v2, -1, v5
	v_fma_f32 v3, -v2, v5, v4
	v_cmp_ge_f32_e64 s[12:13], 0, v3
	v_add_u32_e32 v3, 1, v5
	s_add_i32 s30, s20, 0
	v_cndmask_b32_e64 v2, v5, v2, s[12:13]
	v_fma_f32 v5, -v3, v5, v4
	v_cmp_lt_f32_e64 s[12:13], 0, v5
	v_lshrrev_b32_e32 v5, 1, v10
	v_mov_b32_e32 v11, v1
	v_cndmask_b32_e64 v2, v2, v3, s[12:13]
	v_mul_f32_e32 v3, 0x37800000, v2
	v_cndmask_b32_e32 v2, v2, v3, vcc
	v_cmp_class_f32_e32 vcc, v4, v223
	v_and_b32_e32 v3, 19, v10
	v_and_or_b32 v3, v5, 4, v3
	v_cndmask_b32_e32 v2, v2, v4, vcc
	v_lshlrev_b32_e32 v4, 1, v10
	v_and_b32_e32 v4, 8, v4
	v_or_b32_e32 v6, v3, v4
	v_bitop3_b32 v3, v3, 15, v4 bitop3:0xc8
	v_fmamk_f32 v235, v2, 0x3f804189, v224
	v_sub_u32_e32 v2, v178, v8
	v_lshlrev_b32_e32 v4, 8, v6
	v_or_b32_e32 v6, s2, v210
	v_bitop3_b32 v7, s2, v3, v210 bitop3:0x36
	v_add_u32_e32 v2, s88, v2
	v_lshl_or_b32 v213, v7, 4, v4
	v_bitop3_b32 v7, v6, v3, 2 bitop3:0x36
	v_cvt_f32_i32_e32 v236, v2
	v_sub_co_u32_e64 v2, s[82:83], s24, 1
	v_lshl_or_b32 v215, v7, 4, v4
	v_bitop3_b32 v7, v6, v3, 4 bitop3:0x36
	v_bitop3_b32 v3, v6, v3, 6 bitop3:0x36
	v_readfirstlane_b32 s19, v2
	v_lshlrev_b32_e32 v2, 7, v2
	v_lshl_or_b32 v217, v3, 4, v4
	v_bfe_u32 v3, v10, 1, 3
	v_or_b32_e32 v2, 0x7f, v2
	s_or_b32 s2, s88, 31
	v_lshl_or_b32 v216, v7, 4, v4
	v_lshlrev_b32_e32 v4, 7, v178
	v_bitop3_b32 v5, v210, v5, 7 bitop3:0x78
	v_bitop3_b32 v7, v210, v3, 2 bitop3:0x36
	v_bitop3_b32 v9, v210, v3, 4 bitop3:0x36
	v_bitop3_b32 v3, v210, v3, 6 bitop3:0x36
	v_cvt_f32_u32_e32 v237, v2
	v_cvt_f32_i32_e32 v238, s2
	v_or_b32_e32 v6, 0x4000, v4
	v_lshlrev_b32_e32 v5, 4, v5
	v_lshlrev_b32_e32 v7, 4, v7
	v_lshlrev_b32_e32 v9, 4, v9
	v_lshlrev_b32_e32 v3, 4, v3
	v_or_b32_e32 v231, v5, v6
	v_or_b32_e32 v232, v7, v6
	v_or_b32_e32 v233, v9, v6
	v_or_b32_e32 v234, v3, v6
	v_cmp_eq_u32_e32 vcc, 0, v179
	v_or_b32_e32 v240, v5, v4
	v_or_b32_e32 v241, v7, v4
	v_or_b32_e32 v242, v9, v4
	v_or_b32_e32 v243, v3, v4
	v_mov_b32_e32 v2, v1
	v_mov_b32_e32 v3, v1
	v_mov_b32_e32 v4, v1
	v_mov_b32_e32 v5, v1
	v_mov_b32_e32 v6, v1
	v_mov_b32_e32 v7, v1
	v_mov_b32_e32 v8, v1
	v_mov_b32_e32 v9, v1
	v_mov_b32_e32 v10, v1
	v_mov_b32_e32 v12, v1
	v_mov_b32_e32 v13, v1
	v_mov_b32_e32 v14, v1
	v_mov_b32_e32 v15, v1
	v_mov_b64_e32 v[32:33], v[16:17]
	v_mov_b64_e32 v[48:49], v[16:17]
	v_mov_b64_e32 v[64:65], v[16:17]
	s_mov_b32 s44, 0
	s_mov_b32 s45, 1
	v_cmp_gt_u32_e64 s[12:13], 32, v179
	v_lshl_add_u32 v214, v178, 2, s42
	s_and_b64 s[4:5], s[8:9], vcc
	s_add_i32 s30, s30, 0x20800
	v_mov_b32_e32 v202, v200
	v_mov_b32_e32 v203, v200
	s_mov_b32 s38, 0xff61b1e6
	s_mov_b32 s96, 0x7f61b1e6
	v_mov_b32_e32 v204, 0
	v_mov_b32_e32 v244, 0x7f61b1e6
	s_mov_b32 s31, 0
	v_mov_b64_e32 v[30:31], v[14:15]
	v_mov_b64_e32 v[28:29], v[12:13]
	v_mov_b64_e32 v[26:27], v[10:11]
	v_mov_b64_e32 v[24:25], v[8:9]
	v_mov_b64_e32 v[22:23], v[6:7]
	v_mov_b64_e32 v[20:21], v[4:5]
	v_mov_b64_e32 v[18:19], v[2:3]
	v_mov_b64_e32 v[46:47], v[14:15]
	v_mov_b64_e32 v[44:45], v[12:13]
	v_mov_b64_e32 v[42:43], v[10:11]
	v_mov_b64_e32 v[40:41], v[8:9]
	v_mov_b64_e32 v[38:39], v[6:7]
	v_mov_b64_e32 v[36:37], v[4:5]
	v_mov_b64_e32 v[34:35], v[2:3]
	v_mov_b64_e32 v[62:63], v[14:15]
	v_mov_b64_e32 v[60:61], v[12:13]
	v_mov_b64_e32 v[58:59], v[10:11]
	v_mov_b64_e32 v[56:57], v[8:9]
	v_mov_b64_e32 v[54:55], v[6:7]
	v_mov_b64_e32 v[52:53], v[4:5]
	v_mov_b64_e32 v[50:51], v[2:3]
	v_mov_b32_e32 v248, 0
	s_mov_b32 s36, 0
	s_mov_b32 s37, s24
	v_readfirstlane_b32 s48, v180
	v_readfirstlane_b32 s49, v181
	v_readfirstlane_b32 s50, v182
	v_readfirstlane_b32 s51, v183
	s_nop 3
	s_sub_u32 s48, s48, 0x100
	s_subb_u32 s49, s49, 0
	s_sub_u32 s50, s50, 0x100
	s_subb_u32 s51, s51, 0
	s_nop 1
	v_subrev_u32_e32 v180, s48, v180
	v_subrev_u32_e32 v196, s48, v196
	v_subrev_u32_e32 v182, s50, v182
	v_subrev_u32_e32 v198, s50, v198
	s_add_u32 s48, s48, 0x400
	s_addc_u32 s49, s49, 0
